# P9 state scan software-pipelined: loads of 8 chunks requested 16 chunks ahead into a 4-set register ring (SGPR base + 32-bit offsets), one counted wait per group, stores never waited on; arithmetic an
# speedup vs baseline: 1.0312x; 1.0073x over previous
.LBB0_922:
	s_add_u32 s36, s84, 0x1b00000
	s_addc_u32 s37, s85, 0
	s_add_u32 s38, s84, 0x1db00000
	s_addc_u32 s39, s85, 0
	s_mov_b32 s40, 0
	v_mov_b32_e32 v26, v0
	v_add_u32_e32 v27, 0x8000, v0
	v_add_u32_e32 v28, 0x10000, v0
	v_add_u32_e32 v29, 0x18000, v0
	v_add_u32_e32 v30, 0x20000, v0
	v_add_u32_e32 v31, 0x28000, v0
	v_add_u32_e32 v32, 0x30000, v0
	v_add_u32_e32 v33, 0x38000, v0
	global_load_dword v34, v26, s[36:37]
	global_load_dword v35, v27, s[36:37]
	global_load_dword v36, v28, s[36:37]
	global_load_dword v37, v29, s[36:37]
	global_load_dword v38, v30, s[36:37]
	global_load_dword v39, v31, s[36:37]
	global_load_dword v40, v32, s[36:37]
	global_load_dword v41, v33, s[36:37]
	global_load_dwordx2 v[42:43], v2, s[38:39]
	global_load_dwordx2 v[44:45], v2, s[38:39] offset:512
	global_load_dwordx2 v[46:47], v2, s[38:39] offset:1024
	global_load_dwordx2 v[48:49], v2, s[38:39] offset:1536
	global_load_dwordx2 v[50:51], v2, s[38:39] offset:2048
	global_load_dwordx2 v[52:53], v2, s[38:39] offset:2560
	global_load_dwordx2 v[54:55], v2, s[38:39] offset:3072
	global_load_dwordx2 v[56:57], v2, s[38:39] offset:3584
	v_add_u32_e32 v0, 0x40000, v0
	v_add_u32_e32 v2, 0x1000, v2
	v_mov_b32_e32 v58, v0
	v_add_u32_e32 v59, 0x8000, v0
	v_add_u32_e32 v60, 0x10000, v0
	v_add_u32_e32 v61, 0x18000, v0
	v_add_u32_e32 v62, 0x20000, v0
	v_add_u32_e32 v63, 0x28000, v0
	v_add_u32_e32 v64, 0x30000, v0
	v_add_u32_e32 v65, 0x38000, v0
	global_load_dword v66, v58, s[36:37]
	global_load_dword v67, v59, s[36:37]
	global_load_dword v68, v60, s[36:37]
	global_load_dword v69, v61, s[36:37]
	global_load_dword v70, v62, s[36:37]
	global_load_dword v71, v63, s[36:37]
	global_load_dword v72, v64, s[36:37]
	global_load_dword v73, v65, s[36:37]
	global_load_dwordx2 v[74:75], v2, s[38:39]
	global_load_dwordx2 v[76:77], v2, s[38:39] offset:512
	global_load_dwordx2 v[78:79], v2, s[38:39] offset:1024
	global_load_dwordx2 v[80:81], v2, s[38:39] offset:1536
	global_load_dwordx2 v[82:83], v2, s[38:39] offset:2048
	global_load_dwordx2 v[84:85], v2, s[38:39] offset:2560
	global_load_dwordx2 v[86:87], v2, s[38:39] offset:3072
	global_load_dwordx2 v[88:89], v2, s[38:39] offset:3584
	v_add_u32_e32 v0, 0x40000, v0
	v_add_u32_e32 v2, 0x1000, v2
.Lp9_trip:
	v_mov_b32_e32 v112, v0
	v_add_u32_e32 v113, 0x8000, v0
	v_add_u32_e32 v114, 0x10000, v0
	v_add_u32_e32 v115, 0x18000, v0
	v_add_u32_e32 v116, 0x20000, v0
	v_add_u32_e32 v117, 0x28000, v0
	v_add_u32_e32 v118, 0x30000, v0
	v_add_u32_e32 v119, 0x38000, v0
	global_load_dword v120, v112, s[36:37]
	global_load_dword v121, v113, s[36:37]
	global_load_dword v122, v114, s[36:37]
	global_load_dword v123, v115, s[36:37]
	global_load_dword v124, v116, s[36:37]
	global_load_dword v125, v117, s[36:37]
	global_load_dword v126, v118, s[36:37]
	global_load_dword v127, v119, s[36:37]
	global_load_dwordx2 v[128:129], v2, s[38:39]
	global_load_dwordx2 v[130:131], v2, s[38:39] offset:512
	global_load_dwordx2 v[132:133], v2, s[38:39] offset:1024
	global_load_dwordx2 v[134:135], v2, s[38:39] offset:1536
	global_load_dwordx2 v[136:137], v2, s[38:39] offset:2048
	global_load_dwordx2 v[138:139], v2, s[38:39] offset:2560
	global_load_dwordx2 v[140:141], v2, s[38:39] offset:3072
	global_load_dwordx2 v[142:143], v2, s[38:39] offset:3584
	v_add_u32_e32 v0, 0x40000, v0
	v_add_u32_e32 v2, 0x1000, v2
	s_cmp_lg_u32 s40, 0
	s_cbranch_scc1 .Lp9_w0
	s_waitcnt vmcnt(32)
	s_branch .Lp9_d0
.Lp9_w0:
	s_waitcnt vmcnt(48)
.Lp9_d0:
	v_cvt_pk_bf16_f32 v176, v4, v5
	global_store_dword v26, v176, s[36:37]
	v_lshlrev_b32_e32 v178, 16, v34
	v_and_b32_e32 v179, 0xffff0000, v34
	v_pk_fma_f32 v[4:5], v[4:5], v[42:43], v[178:179]
	v_cvt_pk_bf16_f32 v177, v4, v5
	global_store_dword v27, v177, s[36:37]
	v_lshlrev_b32_e32 v178, 16, v35
	v_and_b32_e32 v179, 0xffff0000, v35
	v_pk_fma_f32 v[4:5], v[4:5], v[44:45], v[178:179]
	v_cvt_pk_bf16_f32 v176, v4, v5
	global_store_dword v28, v176, s[36:37]
	v_lshlrev_b32_e32 v178, 16, v36
	v_and_b32_e32 v179, 0xffff0000, v36
	v_pk_fma_f32 v[4:5], v[4:5], v[46:47], v[178:179]
	v_cvt_pk_bf16_f32 v177, v4, v5
	global_store_dword v29, v177, s[36:37]
	v_lshlrev_b32_e32 v178, 16, v37
	v_and_b32_e32 v179, 0xffff0000, v37
	v_pk_fma_f32 v[4:5], v[4:5], v[48:49], v[178:179]
	v_cvt_pk_bf16_f32 v176, v4, v5
	global_store_dword v30, v176, s[36:37]
	v_lshlrev_b32_e32 v178, 16, v38
	v_and_b32_e32 v179, 0xffff0000, v38
	v_pk_fma_f32 v[4:5], v[4:5], v[50:51], v[178:179]
	v_cvt_pk_bf16_f32 v177, v4, v5
	global_store_dword v31, v177, s[36:37]
	v_lshlrev_b32_e32 v178, 16, v39
	v_and_b32_e32 v179, 0xffff0000, v39
	v_pk_fma_f32 v[4:5], v[4:5], v[52:53], v[178:179]
	v_cvt_pk_bf16_f32 v176, v4, v5
	global_store_dword v32, v176, s[36:37]
	v_lshlrev_b32_e32 v178, 16, v40
	v_and_b32_e32 v179, 0xffff0000, v40
	v_pk_fma_f32 v[4:5], v[4:5], v[54:55], v[178:179]
	v_cvt_pk_bf16_f32 v177, v4, v5
	global_store_dword v33, v177, s[36:37]
	v_lshlrev_b32_e32 v178, 16, v41
	v_and_b32_e32 v179, 0xffff0000, v41
	v_pk_fma_f32 v[4:5], v[4:5], v[56:57], v[178:179]
	v_mov_b32_e32 v144, v0
	v_add_u32_e32 v145, 0x8000, v0
	v_add_u32_e32 v146, 0x10000, v0
	v_add_u32_e32 v147, 0x18000, v0
	v_add_u32_e32 v148, 0x20000, v0
	v_add_u32_e32 v149, 0x28000, v0
	v_add_u32_e32 v150, 0x30000, v0
	v_add_u32_e32 v151, 0x38000, v0
	global_load_dword v152, v144, s[36:37]
	global_load_dword v153, v145, s[36:37]
	global_load_dword v154, v146, s[36:37]
	global_load_dword v155, v147, s[36:37]
	global_load_dword v156, v148, s[36:37]
	global_load_dword v157, v149, s[36:37]
	global_load_dword v158, v150, s[36:37]
	global_load_dword v159, v151, s[36:37]
	global_load_dwordx2 v[160:161], v2, s[38:39]
	global_load_dwordx2 v[162:163], v2, s[38:39] offset:512
	global_load_dwordx2 v[164:165], v2, s[38:39] offset:1024
	global_load_dwordx2 v[166:167], v2, s[38:39] offset:1536
	global_load_dwordx2 v[168:169], v2, s[38:39] offset:2048
	global_load_dwordx2 v[170:171], v2, s[38:39] offset:2560
	global_load_dwordx2 v[172:173], v2, s[38:39] offset:3072
	global_load_dwordx2 v[174:175], v2, s[38:39] offset:3584
	v_add_u32_e32 v0, 0x40000, v0
	v_add_u32_e32 v2, 0x1000, v2
	s_cmp_lg_u32 s40, 0
	s_cbranch_scc1 .Lp9_w1
	s_waitcnt vmcnt(40)
	s_branch .Lp9_d1

.Lp9_d1:
	v_cvt_pk_bf16_f32 v176, v4, v5
	global_store_dword v58, v176, s[36:37]
	v_lshlrev_b32_e32 v178, 16, v66
	v_and_b32_e32 v179, 0xffff0000, v66
	v_pk_fma_f32 v[4:5], v[4:5], v[74:75], v[178:179]
	v_cvt_pk_bf16_f32 v177, v4, v5
	global_store_dword v59, v177, s[36:37]
	v_lshlrev_b32_e32 v178, 16, v67
	v_and_b32_e32 v179, 0xffff0000, v67
	v_pk_fma_f32 v[4:5], v[4:5], v[76:77], v[178:179]
	v_cvt_pk_bf16_f32 v176, v4, v5
	global_store_dword v60, v176, s[36:37]
	v_lshlrev_b32_e32 v178, 16, v68
	v_and_b32_e32 v179, 0xffff0000, v68
	v_pk_fma_f32 v[4:5], v[4:5], v[78:79], v[178:179]
	v_cvt_pk_bf16_f32 v177, v4, v5
	global_store_dword v61, v177, s[36:37]
	v_lshlrev_b32_e32 v178, 16, v69
	v_and_b32_e32 v179, 0xffff0000, v69
	v_pk_fma_f32 v[4:5], v[4:5], v[80:81], v[178:179]
	v_cvt_pk_bf16_f32 v176, v4, v5
	global_store_dword v62, v176, s[36:37]
	v_lshlrev_b32_e32 v178, 16, v70
	v_and_b32_e32 v179, 0xffff0000, v70
	v_pk_fma_f32 v[4:5], v[4:5], v[82:83], v[178:179]
	v_cvt_pk_bf16_f32 v177, v4, v5
	global_store_dword v63, v177, s[36:37]
	v_lshlrev_b32_e32 v178, 16, v71
	v_and_b32_e32 v179, 0xffff0000, v71
	v_pk_fma_f32 v[4:5], v[4:5], v[84:85], v[178:179]
	v_cvt_pk_bf16_f32 v176, v4, v5
	global_store_dword v64, v176, s[36:37]
	v_lshlrev_b32_e32 v178, 16, v72
	v_and_b32_e32 v179, 0xffff0000, v72
	v_pk_fma_f32 v[4:5], v[4:5], v[86:87], v[178:179]
	v_cvt_pk_bf16_f32 v177, v4, v5
	global_store_dword v65, v177, s[36:37]
	v_lshlrev_b32_e32 v178, 16, v73
	v_and_b32_e32 v179, 0xffff0000, v73
	v_pk_fma_f32 v[4:5], v[4:5], v[88:89], v[178:179]
	v_mov_b32_e32 v26, v0
	v_add_u32_e32 v27, 0x8000, v0
	v_add_u32_e32 v28, 0x10000, v0
	v_add_u32_e32 v29, 0x18000, v0
	v_add_u32_e32 v30, 0x20000, v0
	v_add_u32_e32 v31, 0x28000, v0
	v_add_u32_e32 v32, 0x30000, v0
	v_add_u32_e32 v33, 0x38000, v0
	global_load_dword v34, v26, s[36:37]
	global_load_dword v35, v27, s[36:37]
	global_load_dword v36, v28, s[36:37]
	global_load_dword v37, v29, s[36:37]
	global_load_dword v38, v30, s[36:37]
	global_load_dword v39, v31, s[36:37]
	global_load_dword v40, v32, s[36:37]
	global_load_dword v41, v33, s[36:37]
	global_load_dwordx2 v[42:43], v2, s[38:39]
	global_load_dwordx2 v[44:45], v2, s[38:39] offset:512
	global_load_dwordx2 v[46:47], v2, s[38:39] offset:1024
	global_load_dwordx2 v[48:49], v2, s[38:39] offset:1536
	global_load_dwordx2 v[50:51], v2, s[38:39] offset:2048
	global_load_dwordx2 v[52:53], v2, s[38:39] offset:2560
	global_load_dwordx2 v[54:55], v2, s[38:39] offset:3072
	global_load_dwordx2 v[56:57], v2, s[38:39] offset:3584
	v_add_u32_e32 v0, 0x40000, v0
	v_add_u32_e32 v2, 0x1000, v2
	s_waitcnt vmcnt(48)
	v_cvt_pk_bf16_f32 v176, v4, v5
	global_store_dword v112, v176, s[36:37]
	v_lshlrev_b32_e32 v178, 16, v120
	v_and_b32_e32 v179, 0xffff0000, v120
	v_pk_fma_f32 v[4:5], v[4:5], v[128:129], v[178:179]
	v_cvt_pk_bf16_f32 v177, v4, v5
	global_store_dword v113, v177, s[36:37]
	v_lshlrev_b32_e32 v178, 16, v121
	v_and_b32_e32 v179, 0xffff0000, v121
	v_pk_fma_f32 v[4:5], v[4:5], v[130:131], v[178:179]
	v_cvt_pk_bf16_f32 v176, v4, v5
	global_store_dword v114, v176, s[36:37]
	v_lshlrev_b32_e32 v178, 16, v122
	v_and_b32_e32 v179, 0xffff0000, v122
	v_pk_fma_f32 v[4:5], v[4:5], v[132:133], v[178:179]
	v_cvt_pk_bf16_f32 v177, v4, v5
	global_store_dword v115, v177, s[36:37]
	v_lshlrev_b32_e32 v178, 16, v123
	v_and_b32_e32 v179, 0xffff0000, v123
	v_pk_fma_f32 v[4:5], v[4:5], v[134:135], v[178:179]
	v_cvt_pk_bf16_f32 v176, v4, v5
	global_store_dword v116, v176, s[36:37]
	v_lshlrev_b32_e32 v178, 16, v124
	v_and_b32_e32 v179, 0xffff0000, v124
	v_pk_fma_f32 v[4:5], v[4:5], v[136:137], v[178:179]
	v_cvt_pk_bf16_f32 v177, v4, v5
	global_store_dword v117, v177, s[36:37]
	v_lshlrev_b32_e32 v178, 16, v125
	v_and_b32_e32 v179, 0xffff0000, v125
	v_pk_fma_f32 v[4:5], v[4:5], v[138:139], v[178:179]
	v_cvt_pk_bf16_f32 v176, v4, v5
	global_store_dword v118, v176, s[36:37]
	v_lshlrev_b32_e32 v178, 16, v126
	v_and_b32_e32 v179, 0xffff0000, v126
	v_pk_fma_f32 v[4:5], v[4:5], v[140:141], v[178:179]
	v_cvt_pk_bf16_f32 v177, v4, v5
	global_store_dword v119, v177, s[36:37]
	v_lshlrev_b32_e32 v178, 16, v127
	v_and_b32_e32 v179, 0xffff0000, v127
	v_pk_fma_f32 v[4:5], v[4:5], v[142:143], v[178:179]
	v_mov_b32_e32 v58, v0
	v_add_u32_e32 v59, 0x8000, v0
	v_add_u32_e32 v60, 0x10000, v0
	v_add_u32_e32 v61, 0x18000, v0
	v_add_u32_e32 v62, 0x20000, v0
	v_add_u32_e32 v63, 0x28000, v0
	v_add_u32_e32 v64, 0x30000, v0
	v_add_u32_e32 v65, 0x38000, v0
	global_load_dword v66, v58, s[36:37]
	global_load_dword v67, v59, s[36:37]
	global_load_dword v68, v60, s[36:37]
	global_load_dword v69, v61, s[36:37]
	global_load_dword v70, v62, s[36:37]
	global_load_dword v71, v63, s[36:37]
	global_load_dword v72, v64, s[36:37]
	global_load_dword v73, v65, s[36:37]
	global_load_dwordx2 v[74:75], v2, s[38:39]
	global_load_dwordx2 v[76:77], v2, s[38:39] offset:512
	global_load_dwordx2 v[78:79], v2, s[38:39] offset:1024
	global_load_dwordx2 v[80:81], v2, s[38:39] offset:1536
	global_load_dwordx2 v[82:83], v2, s[38:39] offset:2048
	global_load_dwordx2 v[84:85], v2, s[38:39] offset:2560
	global_load_dwordx2 v[86:87], v2, s[38:39] offset:3072
	global_load_dwordx2 v[88:89], v2, s[38:39] offset:3584
	v_add_u32_e32 v0, 0x40000, v0
	v_add_u32_e32 v2, 0x1000, v2
	s_waitcnt vmcnt(48)
	v_cvt_pk_bf16_f32 v176, v4, v5
	global_store_dword v144, v176, s[36:37]
	v_lshlrev_b32_e32 v178, 16, v152
	v_and_b32_e32 v179, 0xffff0000, v152
	v_pk_fma_f32 v[4:5], v[4:5], v[160:161], v[178:179]
	v_cvt_pk_bf16_f32 v177, v4, v5
	global_store_dword v145, v177, s[36:37]
	v_lshlrev_b32_e32 v178, 16, v153
	v_and_b32_e32 v179, 0xffff0000, v153
	v_pk_fma_f32 v[4:5], v[4:5], v[162:163], v[178:179]
	v_cvt_pk_bf16_f32 v176, v4, v5
	global_store_dword v146, v176, s[36:37]
	v_lshlrev_b32_e32 v178, 16, v154
	v_and_b32_e32 v179, 0xffff0000, v154
	v_pk_fma_f32 v[4:5], v[4:5], v[164:165], v[178:179]
	v_cvt_pk_bf16_f32 v177, v4, v5
	global_store_dword v147, v177, s[36:37]
	v_lshlrev_b32_e32 v178, 16, v155
	v_and_b32_e32 v179, 0xffff0000, v155
	v_pk_fma_f32 v[4:5], v[4:5], v[166:167], v[178:179]
	v_cvt_pk_bf16_f32 v176, v4, v5
	global_store_dword v148, v176, s[36:37]
	v_lshlrev_b32_e32 v178, 16, v156
	v_and_b32_e32 v179, 0xffff0000, v156
	v_pk_fma_f32 v[4:5], v[4:5], v[168:169], v[178:179]
	v_cvt_pk_bf16_f32 v177, v4, v5
	global_store_dword v149, v177, s[36:37]
	v_lshlrev_b32_e32 v178, 16, v157
	v_and_b32_e32 v179, 0xffff0000, v157
	v_pk_fma_f32 v[4:5], v[4:5], v[170:171], v[178:179]
	v_cvt_pk_bf16_f32 v176, v4, v5
	global_store_dword v150, v176, s[36:37]
	v_lshlrev_b32_e32 v178, 16, v158
	v_and_b32_e32 v179, 0xffff0000, v158
	v_pk_fma_f32 v[4:5], v[4:5], v[172:173], v[178:179]
	v_cvt_pk_bf16_f32 v177, v4, v5
	global_store_dword v151, v177, s[36:37]
	v_lshlrev_b32_e32 v178, 16, v159
	v_and_b32_e32 v179, 0xffff0000, v159
	v_pk_fma_f32 v[4:5], v[4:5], v[174:175], v[178:179]
	s_add_i32 s40, s40, 1
	s_cmp_lt_u32 s40, 8
	s_cbranch_scc1 .Lp9_trip
	v_add_u32_e32 v6, s26, v6
	v_cmp_lt_i32_e32 vcc, s13, v6
	s_or_b64 s[6:7], vcc, s[6:7]
	v_add_u32_e32 v7, s3, v7
	s_andn2_b64 exec, exec, s[6:7]
	s_cbranch_execnz .LBB0_921
